# baseline (speedup 1.0000x reference)
; __device__ __forceinline__ unsigned xb_ld(unsigned* p)              { return __hip_atomic_load(p, __ATOMIC_RELAXED, __HIP_MEMORY_SCOPE_AGENT); }
;     ...
;     sh[0] = x; sh[1] = xb_ld(&bar[XB_XCNT(x)]); sh[2] = nx;
;   }
;   __syncthreads();
;   XcdBarrier b; b.bar = bar; b.x = __builtin_amdgcn_readfirstlane(sh[0]); b.nloc = __builtin_amdgcn_readfirstlane(sh[1]); b.nx = __builtin_amdgcn_readfirstlane(sh[2]);
;   return b;
; template <unsigned MASK>
; __global__ void __launch_bounds__(NTHR) mega(Params pk) {
;     ...
;   const int ph_lo = pk.ph_lo, ph_hi = pk.ph_hi;
;   __syncthreads();
;   PRef p{smem + PARAMS_LDS_OFF};
;     ...
;   unsigned nbar = 0;
;   for (int ph = ph_lo; ph < ph_hi; ++ph) {
.LBB0_18:
	s_or_b64 exec, exec, s[2:3]
	s_mov_b64 s[2:3], src_shared_base
	s_add_i32 s2, 0, 0x23ff0
	s_cmp_lg_u32 s2, -1
	s_cselect_b32 s2, s2, 0
	s_cselect_b32 s4, s3, 0
	v_mov_b32_e32 v2, s2
	s_add_i32 s2, 0, 0x23ff4
	s_cmp_lg_u32 s2, -1
	v_mov_b32_e32 v3, s4
	s_cselect_b32 s2, s2, 0
	s_cselect_b32 s4, s3, 0
	s_waitcnt lgkmcnt(0)
	s_barrier
	flat_load_dword v1, v[2:3] sc0 sc1
	s_waitcnt vmcnt(0)
	v_mov_b32_e32 v2, s2
	v_mov_b32_e32 v3, s4
	s_add_i32 s2, 0, 0x23ff8
	flat_load_dword v4, v[2:3] sc0 sc1
	s_waitcnt vmcnt(0)
	s_cmp_lg_u32 s2, -1
	s_cselect_b32 s2, s2, 0
	s_cselect_b32 s3, s3, 0
	v_mov_b32_e32 v2, s2
	v_mov_b32_e32 v3, s3
	flat_load_dword v2, v[2:3] sc0 sc1
	s_waitcnt vmcnt(0)
	s_mov_b32 s87, 0
	s_waitcnt lgkmcnt(0)
	v_readfirstlane_b32 s2, v1
	v_readfirstlane_b32 s3, v4
	s_nop 1
	v_writelane_b32 v254, s3, 9
	v_writelane_b32 v254, s30, 10
	s_cmp_ge_i32 s30, s31
	v_readfirstlane_b32 s3, v2
	v_writelane_b32 v254, s31, 11
	s_nop 0
	v_writelane_b32 v254, s3, 12
	s_mov_b32 s3, 0
	v_writelane_b32 v255, s3, 61
	s_cbranch_scc1 .LBB0_1226
	v_readlane_b32 s5, v254, 0
	s_lshl_b32 s3, s5, 9
	v_writelane_b32 v254, s3, 13
	v_lshrrev_b32_e32 v1, 20, v0
	v_readlane_b32 s6, v254, 1
	s_lshl_b32 s48, s6, 9
	s_cmpk_lt_i32 s5, 0x400
	s_cselect_b64 s[8:9], -1, 0
	s_ashr_i32 s3, s5, 31
	s_lshr_b32 s3, s3, 29
	v_readlane_b32 s7, v254, 2
	v_writelane_b32 v254, s8, 14
	s_add_i32 s3, s5, s3
	s_ashr_i32 s4, s3, 3
	v_writelane_b32 v254, s9, 15
	s_and_b32 s3, s3, -8
	v_writelane_b32 v254, s4, 16
	s_sub_i32 s3, s5, s3
	v_writelane_b32 v254, s3, 17
	s_lshr_b32 s3, s3, 31
	s_cmpk_lt_i32 s5, 0xa40
	v_writelane_b32 v254, s3, 18
	s_cselect_b64 s[8:9], -1, 0
	s_lshl_b32 s7, s5, 3
	s_lshl_b32 s3, s6, 3
	v_writelane_b32 v254, s8, 19
	s_cmpk_lt_i32 s5, 0x100
	v_lshrrev_b32_e32 v0, 10, v0
	v_writelane_b32 v254, s9, 20
	s_cselect_b64 s[8:9], -1, 0
	s_lshl_b32 s4, s2, 6
	s_add_i32 s86, s4, 0x500
	v_writelane_b32 v254, s3, 21
	s_lshl_b64 s[2:3], s[86:87], 2
	v_writelane_b32 v254, s8, 22
	s_add_u32 s2, s0, s2
	s_addc_u32 s3, s1, s3
	v_writelane_b32 v254, s9, 23
	v_writelane_b32 v254, s2, 24
	s_add_i32 s86, s4, 0x900
	v_or_b32_e32 v0, v0, v1
	v_writelane_b32 v254, s3, 25
	s_lshl_b64 s[2:3], s[86:87], 2
	s_add_u32 s0, s0, s2
	s_addc_u32 s1, s1, s3
	v_writelane_b32 v254, s0, 26
	v_or_b32_e32 v2, s5, v171
	v_mbcnt_lo_u32_b32 v3, -1, 0
	v_writelane_b32 v254, s1, 27
	s_add_u32 s0, s26, 0x2901200
	s_addc_u32 s1, s27, 0
	v_writelane_b32 v254, s0, 28
	v_mbcnt_hi_u32_b32 v193, -1, v3
	v_mov_b32_e32 v1, 0
	v_writelane_b32 v254, s1, 29
	s_add_u32 s0, s26, 0x2904400
	s_addc_u32 s1, s27, 0
	v_writelane_b32 v254, s0, 30
	s_mov_b32 s80, 0xc2200000
	s_mov_b32 s42, 0xc2080000
	v_writelane_b32 v254, s1, 31
	s_add_u32 s0, s26, 0x2904500
	s_addc_u32 s1, s27, 0
	v_writelane_b32 v254, s0, 32
	s_mov_b32 s92, 0xc2000000
	v_and_b32_e32 v3, 64, v193
	v_writelane_b32 v254, s1, 33
	v_mov_b32_e32 v190, 0x358637bd
	v_readlane_b32 s0, v254, 10
	v_readlane_b32 s1, v254, 11
	s_cmp_gt_i32 s0, -1
	s_cselect_b64 s[0:1], -1, 0
	v_writelane_b32 v254, s0, 34
	s_lshl_b32 s3, s6, 12
	v_mov_b32_e32 v191, 1
	v_writelane_b32 v254, s1, 35
	s_movk_i32 s0, 0x3ff
	v_and_or_b32 v0, v0, s0, v171
	s_lshl_b32 s0, s5, 12
	v_writelane_b32 v254, s0, 36
	s_lshl_b32 s0, s5, 4
	v_writelane_b32 v254, s0, 37
	s_lshl_b32 s0, s6, 4
	v_writelane_b32 v254, s0, 38
	s_lshl_b32 s1, s6, 8
	s_lshl_b32 s0, s5, 8
	v_writelane_b32 v254, s1, 39
	v_writelane_b32 v254, s0, 40
	s_or_b32 s0, s0, 15
	v_writelane_b32 v254, s0, 41
	v_writelane_b32 v254, s7, 42
	s_add_i32 s0, s7, 0x7be00
	v_writelane_b32 v254, s0, 43
	s_lshl_b32 s0, s5, 6
	v_writelane_b32 v254, s0, 44
	s_lshl_b32 s0, s6, 6
	v_writelane_b32 v254, s0, 45
	s_add_i32 s0, 0, 0x22040
	v_writelane_b32 v254, s0, 46
	s_add_i32 s0, 0, 0x22080
	v_writelane_b32 v254, s0, 47
	s_add_i32 s0, 0, 0x8880
	v_writelane_b32 v254, s0, 48
	s_add_i32 s0, 0, 0x4400
	v_writelane_b32 v254, s0, 49
	s_add_i32 s0, 0, 0x18000
	v_writelane_b32 v254, s0, 50
	s_add_i32 s0, 0, 0x1c000
	v_writelane_b32 v254, s0, 51
	s_mov_b32 s0, 0
	v_writelane_b32 v254, s0, 52
	v_cmp_eq_u32_e64 s[0:1], 0, v2
	v_mov_b32_e32 v192, 0x260
	s_brev_b32 s78, -2
	v_writelane_b32 v254, s0, 53
	s_mov_b32 s81, 0xc2240000
	s_mov_b32 s43, 0xc20c0000
	v_writelane_b32 v254, s1, 54
	v_cmp_eq_u32_e64 s[0:1], 0, v0
	s_mov_b32 s93, 0xc2040000
	v_mov_b32_e32 v145, 0xc1f00000
	v_writelane_b32 v254, s0, 55
	s_mov_b32 s79, 0x20000
	v_add_u32_e32 v195, 64, v3
	v_xor_b32_e32 v253, 16, v193
	v_xor_b32_e32 v210, 8, v193
	v_mov_b32_e32 v194, 0x200
	v_mov_b32_e32 v211, 0x4000
	v_mov_b32_e32 v252, 0x42800000
	v_not_b32_e32 v208, 63
	v_mov_b32_e32 v209, 0xf149f2ca
	v_mov_b32_e32 v244, v1
	v_mov_b32_e32 v245, v1
	v_mov_b32_e32 v246, v1
	v_mov_b32_e32 v247, v1
	s_mov_b32 s49, 0xee00000
	s_movk_i32 s50, 0x1080
	s_movk_i32 s33, 0x110
	s_movk_i32 s96, 0x1600
	s_movk_i32 s51, 0x7fff
	v_writelane_b32 v254, s1, 56
	s_mov_b32 s85, s48
	s_mov_b32 s2, s3
	s_branch .LBB0_24

;   __device__ __forceinline__ const float* in(int i) const { return reinterpret_cast<const float*>(ld64(i * 8)); }
;   __device__ __forceinline__ unsigned char* ws() const { return reinterpret_cast<unsigned char*>(ld64(27 * 8)); }
; __device__ __forceinline__ int opaque_tid() { int t = threadIdx.x; asm volatile("" : "+v"(t)); return t; }
; __device__ __forceinline__ void phase_cache(const PRef& p, char* lds) {
;   const int tidx = opaque_tid();
;   bf16* ks = (bf16*)(p.ws() + WS_KS);
;   bf16* vts = (bf16*)(p.ws() + WS_VTS);
;   const float* c_sbk = p.in(2); const float* c_sbv = p.in(3); const float* c_dk = p.in(4); const float* c_dv = p.in(5);
;   const int gtid = blockIdx.x * NTHR + tidx, gsz = gridDim.x * NTHR;
;   for (int u = gtid; u < 8 * PAST * 256; u += gsz) {
;     int c4 = u & 255, pos = (u >> 8) & (PAST - 1), b = u >> 19;
;     const float* src = (c4 < 128) ? c_sbk + ((size_t)(b * PAST + pos) * 512 + c4 * 4) : c_dk + ((size_t)(b * PAST + pos) * 512 + (c4 - 128) * 4);
;     const f32x4v v = __builtin_nontemporal_load(reinterpret_cast<const f32x4v*>(src));
;     u32x2 w = {cvtpk(v[0], v[1]), cvtpk(v[2], v[3])};
;     *reinterpret_cast<u32x2*>(ks + ((size_t)(b * SPAD + pos) * 1024 + c4 * 4)) = w;
;   }
.LBB0_284:
	s_and_b64 vcc, exec, s[0:1]
	s_cbranch_vccz .LBB0_302
	v_readlane_b32 s4, v254, 10
	s_cmp_gt_i32 s4, 2
	s_mov_b64 s[0:1], -1
	v_readlane_b32 s5, v254, 11
	s_cbranch_scc0 .LBB0_314
	s_cmp_gt_i32 s4, 3
	s_cbranch_scc0 .LBB0_304
	v_readlane_b32 s4, v254, 0
	v_readlane_b32 s5, v255, 61
	s_bitcmp1_b32 s4, 0
	s_cselect_b32 s4, 1, 0
	s_cmp_eq_u32 s5, 0
	s_cselect_b32 s4, s4, 0
	s_cmp_lg_u32 s4, 0
	s_cbranch_scc1 .Lmy_pc_skip
.Lmy_pc_body:
	v_readlane_b32 s0, v254, 5
	s_mov_b64 s[4:5], src_shared_base
	s_cmp_lg_u32 s0, -1
	s_cselect_b32 s0, s0, 0
	s_cselect_b32 s1, s5, 0
	v_mov_b32_e32 v20, v171
	v_mov_b64_e32 v[2:3], s[0:1]
	v_readlane_b32 s0, v254, 6
	flat_load_dword v0, v[2:3] sc0 sc1
	s_waitcnt vmcnt(0)
	s_cmp_lg_u32 s0, -1
	s_cselect_b32 s0, s0, 0
	s_cselect_b32 s1, s5, 0
	v_mov_b64_e32 v[4:5], s[0:1]
	flat_load_dword v6, v[4:5] sc0 sc1
	s_waitcnt vmcnt(0)
	flat_load_dword v7, v[2:3] sc0 sc1
	s_waitcnt vmcnt(0)
	flat_load_dword v4, v[4:5] sc0 sc1
	s_waitcnt vmcnt(0) lgkmcnt(0)
	v_readfirstlane_b32 s0, v0
	s_add_u32 s0, s0, 0xcd00000
	v_readfirstlane_b32 s1, v6
	s_addc_u32 s1, s1, 0
	s_add_i32 s4, 0, 0x23f10
	s_cmp_lg_u32 s4, -1
	s_cselect_b32 s4, s4, 0
	s_cselect_b32 s6, s5, 0
	s_add_i32 s7, 0, 0x23f14
	s_cmp_lg_u32 s7, -1
	v_mov_b32_e32 v2, s4
	v_mov_b32_e32 v3, s6
	s_cselect_b32 s4, s7, 0
	s_cselect_b32 s6, s5, 0
	s_add_i32 s7, 0, 0x23f18
	s_cmp_lg_u32 s7, -1
	flat_load_dword v0, v[2:3] sc0 sc1
	s_waitcnt vmcnt(0)
	v_mov_b32_e32 v2, s4
	v_mov_b32_e32 v3, s6
	s_cselect_b32 s4, s7, 0
	s_cselect_b32 s6, s5, 0
	s_add_i32 s7, 0, 0x23f1c
	s_cmp_lg_u32 s7, -1
	flat_load_dword v5, v[2:3] sc0 sc1
	s_waitcnt vmcnt(0)
	v_mov_b32_e32 v2, s4
	v_mov_b32_e32 v3, s6
	s_cselect_b32 s4, s7, 0
	s_cselect_b32 s6, s5, 0
	s_add_i32 s7, 0, 0x23f20
	s_cmp_lg_u32 s7, -1
	flat_load_dword v6, v[2:3] sc0 sc1
	s_waitcnt vmcnt(0)
	v_mov_b32_e32 v2, s4
	v_mov_b32_e32 v3, s6
	s_cselect_b32 s4, s7, 0
	s_cselect_b32 s6, s5, 0
	s_add_i32 s7, 0, 0x23f24
	s_cmp_lg_u32 s7, -1
	flat_load_dword v9, v[2:3] sc0 sc1
	s_waitcnt vmcnt(0)
	v_mov_b32_e32 v2, s4
	v_mov_b32_e32 v3, s6
	s_cselect_b32 s4, s7, 0
	s_cselect_b32 s6, s5, 0
	s_add_i32 s7, 0, 0x23f28
	s_cmp_lg_u32 s7, -1
	flat_load_dword v10, v[2:3] sc0 sc1
	s_waitcnt vmcnt(0)
	v_mov_b32_e32 v2, s4
	v_mov_b32_e32 v3, s6
	s_cselect_b32 s4, s7, 0
	s_cselect_b32 s6, s5, 0
	s_add_i32 s7, 0, 0x23f2c
	s_cmp_lg_u32 s7, -1
	flat_load_dword v11, v[2:3] sc0 sc1
	s_waitcnt vmcnt(0)
	v_mov_b32_e32 v2, s4
	v_mov_b32_e32 v3, s6
	s_cselect_b32 s4, s7, 0
	s_cselect_b32 s5, s5, 0
	flat_load_dword v12, v[2:3] sc0 sc1
	s_waitcnt vmcnt(0)
	v_mov_b32_e32 v2, s4
	v_mov_b32_e32 v3, s5
	flat_load_dword v2, v[2:3] sc0 sc1
	s_waitcnt vmcnt(0)
	v_readlane_b32 s4, v254, 13
	v_readfirstlane_b32 s14, v7
	v_readfirstlane_b32 s15, v4
	v_add_u32_e32 v8, s4, v20
	s_mov_b32 s4, 0x400000
	v_cmp_gt_i32_e32 vcc, s4, v8
	s_waitcnt lgkmcnt(0)
	v_readfirstlane_b32 s6, v0
	v_readfirstlane_b32 s7, v5
	v_readfirstlane_b32 s10, v6
	v_readfirstlane_b32 s11, v9
	v_readfirstlane_b32 s8, v10
	v_readfirstlane_b32 s9, v11
	v_readfirstlane_b32 s12, v12
	v_readfirstlane_b32 s13, v2
	s_and_saveexec_b64 s[4:5], vcc
	s_movk_i32 s18, 0x840
	s_cbranch_execz .LBB0_290
	v_mov_b32_e32 v0, 4
	v_lshlrev_b32_sdwa v0, v0, v20 dst_sel:DWORD dst_unused:UNUSED_PAD src0_sel:DWORD src1_sel:BYTE_0
	v_lshl_add_u64 v[2:3], s[8:9], 0, v[0:1]
	v_lshl_add_u64 v[4:5], s[6:7], 0, v[0:1]
	v_mov_b32_e32 v0, 3
	s_movk_i32 s16, 0x80
	v_lshlrev_b32_sdwa v0, v0, v20 dst_sel:DWORD dst_unused:UNUSED_PAD src0_sel:DWORD src1_sel:BYTE_0
	v_cmp_lt_u32_sdwa vcc, v20, s16 src0_sel:BYTE_0 src1_sel:DWORD
	v_lshl_add_u64 v[6:7], s[0:1], 0, v[0:1]
	s_mov_b64 s[8:9], 0
	v_mov_b32_e32 v0, v8
	s_mov_b64 s[24:25], vcc
	s_movk_i32 s6, 0xf800
	s_mov_b32 s7, -1
	v_lshl_add_u64 v[42:43], v[2:3], 0, s[6:7]
	v_cndmask_b32_e32 v43, v43, v5, vcc
	v_cndmask_b32_e32 v42, v42, v4, vcc
	s_mul_i32 s19, s48, 7
	s_lshl_b32 s20, s48, 3
	s_mov_b32 s21, 0x400000
	s_mov_b64 s[26:27], exec

; template <int MODE>
; __device__ __forceinline__ void phase_rows(const PRef& p, const float* __restrict__ vsrc, const float* __restrict__ g1, const float* __restrict__ g2, float coef, int nsplit) {
;   const int tidx = opaque_tid();
;   const int lane = tidx & 63, wave = tidx >> 6;
;   bf16* xn = (bf16*)(p.ws() + WS_XN);
;   float* hbuf = p.out() + O_Y;
;   const float* xp = p.in(0); const float* xs_ = p.in(1);
;   for (int row = blockIdx.x * 8 + wave; row < MT; row += gridDim.x * 8) {
;     float4 h[4];
;     if (MODE == 0) {
;       const float4* xs = reinterpret_cast<const float4*>(row < MP ? xp + (size_t)row * DM : xs_ + (size_t)(row - MP) * DM);
; #pragma unroll
;       for (int i = 0; i < 4; ++i) { const f32x4v t = __builtin_nontemporal_load(reinterpret_cast<const f32x4v*>(xs) + lane + 64 * i); h[i] = make_float4(t[0], t[1], t[2], t[3]); }
;     } else {
;       const u32x2* vs = reinterpret_cast<const u32x2*>(reinterpret_cast<const bf16*>(vsrc) + (size_t)row * DM);
;       const float4* bs = (MODE == 1) ? reinterpret_cast<const float4*>(row < MP ? xp + (size_t)row * DM : xs_ + (size_t)(row - MP) * DM) : reinterpret_cast<const float4*>(hbuf + (size_t)row * DM);
;       float4 v[4]; float ss = 0.f;
;       if (row < MP) {
; #pragma unroll
;         for (int i = 0; i < 4; ++i) { const u32x2 q = vs[lane + 64 * i];
;           v[i] = make_float4(__uint_as_float(q[0] << 16), __uint_as_float(q[0] & 0xffff0000u), __uint_as_float(q[1] << 16), __uint_as_float(q[1] & 0xffff0000u)); }
;       } else {
;         const float4* ps = reinterpret_cast<const float4*>((const float*)(p.ws() + WS_PART) + (size_t)(row - MP) * DM);
; #pragma unroll
;         for (int i = 0; i < 4; ++i) v[i] = ps[lane + 64 * i];
;         for (int k = 1; k < nsplit; ++k) {
; #pragma unroll
;           for (int i = 0; i < 4; ++i) { float4 t = ps[(size_t)k * (MS * DM / 4) + lane + 64 * i]; v[i].x += t.x; v[i].y += t.y; v[i].z += t.z; v[i].w += t.w; }
;         }
;       }
; template <unsigned MASK>
; __global__ void __launch_bounds__(NTHR) mega(Params pk) {
;     ...
;         case 3: if constexpr ((MASK >> 3) & 1) {
;           for (int rep = 0; rep < 1 + DUP_ROWS; ++rep) {
;             if (rep) xcd_barrier(xb, nbar++);
;             phase_rows<1>(p, (const float*)(p.ws() + WS_FF), p.in(10), p.in(11), 0.5f, SPLIT_FF);
;           }
.LBB0_303:
	s_mov_b64 s[0:1], 0
	s_mov_b64 s[8:9], -1
	s_waitcnt lgkmcnt(0)
	s_barrier
	v_readlane_b32 s4, v255, 61
	s_cmp_lg_u32 s4, 0
	s_cbranch_scc1 .Lmy_pc_done
	s_branch .LBB0_304
.Lmy_pc_skip:
	s_mov_b64 s[0:1], 0
	s_mov_b64 s[8:9], -1
.LBB0_304:
	s_and_b64 vcc, exec, s[0:1]
	s_cbranch_vccz .LBB0_313
	v_readlane_b32 s0, v254, 5
	s_cmp_lg_u32 s0, -1
	s_mov_b64 s[12:13], src_shared_base
	s_cselect_b32 s0, s0, 0
	s_cselect_b32 s1, s13, 0
	v_mov_b64_e32 v[2:3], s[0:1]
	v_readlane_b32 s0, v254, 6
	s_cmp_lg_u32 s0, -1
	s_cselect_b32 s0, s0, 0
	s_cselect_b32 s1, s13, 0
	v_mov_b64_e32 v[4:5], s[0:1]
	flat_load_dword v0, v[2:3] sc0 sc1
	s_waitcnt vmcnt(0)
	flat_load_dword v6, v[4:5] sc0 sc1
	s_waitcnt vmcnt(0)
	s_add_i32 s4, 0, 0x23f50
	s_cmp_lg_u32 s4, -1
	s_cselect_b32 s4, s4, 0
	s_cselect_b32 s5, s13, 0
	v_mov_b32_e32 v7, s5
	s_waitcnt lgkmcnt(0)
	v_readfirstlane_b32 s0, v0
	v_readfirstlane_b32 s1, v6
	v_mov_b32_e32 v6, s4
	s_add_i32 s4, 0, 0x23f54
	s_cmp_lg_u32 s4, -1
	s_cselect_b32 s4, s4, 0
	s_cselect_b32 s5, s13, 0
	flat_load_dword v0, v[6:7] sc0 sc1
	s_waitcnt vmcnt(0)
	v_mov_b32_e32 v6, s4
	v_mov_b32_e32 v7, s5
	flat_load_dword v6, v[6:7] sc0 sc1
	s_waitcnt vmcnt(0)
	s_add_i32 s6, 0, 0x23f58
	s_cmp_lg_u32 s6, -1
	s_cselect_b32 s6, s6, 0
	s_cselect_b32 s7, s13, 0
	v_mov_b32_e32 v7, s7
	s_waitcnt lgkmcnt(0)
	v_readfirstlane_b32 s4, v0
	v_readfirstlane_b32 s5, v6
	v_mov_b32_e32 v6, s6
	flat_load_dword v0, v[6:7] sc0 sc1
	s_waitcnt vmcnt(0)
	s_add_i32 s6, 0, 0x23f5c
	s_cmp_lg_u32 s6, -1
	s_cselect_b32 s6, s6, 0
	s_cselect_b32 s7, s13, 0
	v_mov_b32_e32 v6, s6
	v_mov_b32_e32 v7, s7
	flat_load_dword v6, v[6:7] sc0 sc1
	s_waitcnt vmcnt(0)
	s_add_i32 s10, 0, 0x23fd0
	s_cmp_lg_u32 s10, -1
	s_cselect_b32 s10, s10, 0
	s_cselect_b32 s11, s13, 0
	s_waitcnt lgkmcnt(0)
	v_readfirstlane_b32 s16, v0
	v_mov_b32_e32 v0, v171
	flat_load_dword v2, v[2:3] sc0 sc1
	s_waitcnt vmcnt(0)
	flat_load_dword v3, v[4:5] sc0 sc1
	s_waitcnt vmcnt(0)
	v_readfirstlane_b32 s17, v6
	v_ashrrev_i32_e32 v6, 6, v0
	s_waitcnt lgkmcnt(0)
	v_readfirstlane_b32 s6, v2
	v_mov_b32_e32 v2, s10
	s_add_i32 s10, 0, 0x23fd4
	s_cmp_lg_u32 s10, -1
	v_readfirstlane_b32 s7, v3
	v_mov_b32_e32 v3, s11
	s_cselect_b32 s10, s10, 0
	s_cselect_b32 s11, s13, 0
	flat_load_dword v4, v[2:3] sc0 sc1
	s_waitcnt vmcnt(0)
	v_mov_b32_e32 v2, s10
	v_mov_b32_e32 v3, s11
	flat_load_dword v2, v[2:3] sc0 sc1
	s_waitcnt vmcnt(0)
	s_add_i32 s10, 0, 0x23f00
	s_cmp_lg_u32 s10, -1
	s_cselect_b32 s10, s10, 0
	s_cselect_b32 s11, s13, 0
	v_mov_b32_e32 v3, s11
	s_waitcnt lgkmcnt(0)
	v_readfirstlane_b32 s18, v4
	v_readfirstlane_b32 s19, v2
	v_mov_b32_e32 v2, s10
	s_add_i32 s10, 0, 0x23f04
	s_cmp_lg_u32 s10, -1
	s_cselect_b32 s10, s10, 0
	s_cselect_b32 s11, s13, 0
	flat_load_dword v4, v[2:3] sc0 sc1
	s_waitcnt vmcnt(0)
	v_mov_b32_e32 v2, s10
	v_mov_b32_e32 v3, s11
	flat_load_dword v2, v[2:3] sc0 sc1
	s_waitcnt vmcnt(0)
	s_add_i32 s12, 0, 0x23f08
	s_cmp_lg_u32 s12, -1
	s_cselect_b32 s12, s12, 0
	s_cselect_b32 s14, s13, 0
	v_mov_b32_e32 v3, s14
	v_readlane_b32 s14, v254, 42
	s_waitcnt lgkmcnt(0)
	v_readfirstlane_b32 s10, v4
	v_add_u32_e32 v58, s14, v6
	s_movk_i32 s14, 0x4100
	v_readfirstlane_b32 s11, v2
	v_mov_b32_e32 v2, s12
	s_add_i32 s12, 0, 0x23f0c
	s_cmp_lg_u32 s12, -1
	s_cselect_b32 s12, s12, 0
	s_cselect_b32 s13, s13, 0
	flat_load_dword v4, v[2:3] sc0 sc1
	s_waitcnt vmcnt(0)
	v_mov_b32_e32 v2, s12
	v_mov_b32_e32 v3, s13
	flat_load_dword v2, v[2:3] sc0 sc1
	s_waitcnt vmcnt(0)
	v_cmp_gt_i32_e32 vcc, s14, v58
	s_waitcnt lgkmcnt(0)
	v_readfirstlane_b32 s12, v4
	v_readfirstlane_b32 s13, v2
	s_and_saveexec_b64 s[14:15], vcc
	s_cbranch_execz .LBB0_312
	v_and_b32_e32 v60, 63, v0
	v_lshlrev_b32_e32 v0, 4, v60
	v_lshl_add_u64 v[62:63], s[16:17], 0, v[0:1]
	v_lshl_add_u64 v[18:19], s[4:5], 0, v[0:1]
	flat_load_dwordx4 v[2:5], v[62:63]
	flat_load_dwordx4 v[228:231], v[62:63] offset:1024
	flat_load_dwordx4 v[232:235], v[62:63] offset:2048
	flat_load_dwordx4 v[236:239], v[62:63] offset:3072
	flat_load_dwordx4 v[6:9], v[18:19]
	flat_load_dwordx4 v[10:13], v[18:19] offset:1024
	flat_load_dwordx4 v[14:17], v[18:19] offset:2048
	s_nop 0
	flat_load_dwordx4 v[18:21], v[18:19] offset:3072
	v_xor_b32_e32 v22, 32, v193
	v_cmp_lt_i32_e32 vcc, v22, v195
	v_lshl_add_u64 v[64:65], s[18:19], 0, v[0:1]
	v_lshlrev_b32_e32 v0, 3, v60
	v_cndmask_b32_e32 v22, v193, v22, vcc
	v_cmp_lt_i32_e32 vcc, v253, v195
	v_lshlrev_b32_e32 v61, 2, v22
	s_mov_b64 s[16:17], 0
	v_cndmask_b32_e32 v22, v193, v253, vcc
	v_cmp_lt_i32_e32 vcc, v210, v195
	v_lshlrev_b32_e32 v84, 2, v22
	s_nop 0
	v_cndmask_b32_e32 v22, v193, v210, vcc
	v_lshlrev_b32_e32 v85, 2, v22
	v_xor_b32_e32 v22, 4, v193
	v_cmp_lt_i32_e32 vcc, v22, v195
	s_nop 1
	v_cndmask_b32_e32 v22, v193, v22, vcc
	v_lshlrev_b32_e32 v86, 2, v22
	v_xor_b32_e32 v22, 2, v193
	v_cmp_lt_i32_e32 vcc, v22, v195
	s_nop 1
	v_cndmask_b32_e32 v22, v193, v22, vcc
	v_lshlrev_b32_e32 v87, 2, v22
	v_xor_b32_e32 v22, 1, v193
	v_cmp_lt_i32_e32 vcc, v22, v195
	s_nop 1
	v_cndmask_b32_e32 v22, v193, v22, vcc
	v_lshlrev_b32_e32 v88, 2, v22
	v_lshl_add_u64 v[22:23], s[0:1], 0, v[0:1]
	s_mov_b64 s[0:1], 0x4b00000
	v_lshl_add_u64 v[66:67], v[22:23], 0, s[0:1]
	v_lshl_add_u64 v[22:23], s[6:7], 0, v[0:1]
	s_mov_b64 s[0:1], 0x2a00000
	v_lshl_add_u64 v[68:69], v[22:23], 0, s[0:1]
	s_branch .LBB0_308

;   __device__ __forceinline__ const float* in(int i) const { return reinterpret_cast<const float*>(ld64(i * 8)); }
;   __device__ __forceinline__ unsigned char* ws() const { return reinterpret_cast<unsigned char*>(ld64(27 * 8)); }
; __device__ __forceinline__ void phase_convert(const PRef& p) {
;   unsigned char* ws = p.ws();
;   constexpr int U0 = 704, U1 = U0 + 352, U2 = U1 + 704, U3 = U2 + 352, U4 = U3 + 384, U5 = U4 + 128;
;   for (int u = blockIdx.x; u < U5; u += gridDim.x) {
;     if (u < U0)      convert_weight(p.in(7), p.in(8), true, 1024, DFF, 5632, (bf16*)(ws + WS_W1A), u);
;     else if (u < U1) convert_weight(p.in(9), nullptr, false, DFF, 1024, 1024, (bf16*)(ws + WS_WD1), u - U0);
;     else if (u < U2) convert_weight(p.in(21), p.in(22), true, 1024, DFF, 5632, (bf16*)(ws + WS_W1B), u - U1);
;     else if (u < U3) convert_weight(p.in(23), nullptr, false, DFF, 1024, 1024, (bf16*)(ws + WS_WD2), u - U2);
;     else if (u < U4) convert_weight(p.in(12), nullptr, false, 1024, 3072, 3072, (bf16*)(ws + WS_WIN), u - U3);
;     else             convert_weight(p.in(18), nullptr, false, 1024, 1024, 1024, (bf16*)(ws + WS_WOUT), u - U4);
;   }
; template <unsigned MASK>
; __global__ void __launch_bounds__(NTHR) mega(Params pk) {
;     ...
;     if (is_gemm) {
;       if constexpr ((MASK & 0x356u) != 0) {
;         if (ph == 4) phase_cache(p, smem);
.LBB0_1138:
	v_readlane_b32 s0, v254, 10
	s_cmp_lg_u32 s0, 4
	s_cbranch_scc1 .Lmy_pc_done
	v_readlane_b32 s0, v254, 0
	s_bitcmp1_b32 s0, 0
	s_cbranch_scc0 .Lmy_pc_done
	s_mov_b32 s0, 1
	v_writelane_b32 v255, s0, 61
	s_mov_b32 s48, s85
	s_mov_b32 s3, s2
	s_mov_b32 s49, 0xee00000
	s_movk_i32 s50, 0x1080
	s_movk_i32 s51, 0x7fff
	s_waitcnt vmcnt(0) lgkmcnt(0)
	s_branch .Lmy_pc_body
.Lmy_pc_done:
	s_mov_b32 s0, 0
	v_writelane_b32 v255, s0, 61
	v_readlane_b32 s0, v254, 10
	v_readlane_b32 s1, v254, 0
	s_mov_b32 s16, -1
	s_mov_b32 s17, 0
	s_mov_b32 s101, 0
	s_cmp_eq_u32 s0, 1
	s_cselect_b32 s16, 0x96, s16
	s_cselect_b32 s17, 0x2c0, s17
	s_cselect_b32 s101, 0x580, s101
	s_cmp_eq_u32 s0, 6
	s_cselect_b32 s16, 0x10, s16
	s_cselect_b32 s17, 0x580, s17
	s_cselect_b32 s101, 0x6e0, s101
	s_cmp_eq_u32 s0, 8
	s_cselect_b32 s16, 0x96, s16
	s_cselect_b32 s17, 0x6e0, s17
	s_cselect_b32 s101, 0x840, s101
	s_cmp_eq_u32 s0, 2
	s_cselect_b32 s16, 0x2c, s16
	s_cselect_b32 s17, 0x840, s17
	s_cselect_b32 s101, 0x9c0, s101
	s_cmp_eq_u32 s0, 4
	s_cselect_b32 s16, 0x30, s16
	s_cselect_b32 s17, 0x9c0, s17
	s_cselect_b32 s101, 0xa40, s101
	s_cmp_lt_u32 s1, s16
	s_cbranch_scc1 .Lmy_cv_return
	v_readlane_b32 s100, v254, 1
	s_sub_i32 s100, s100, s16
	s_sub_i32 s18, s1, s16
	s_add_i32 s18, s18, s17
	s_cmp_ge_i32 s18, s101
	s_cbranch_scc1 .Lmy_cv_return
	s_lshl_b32 s17, s18, 8
	s_or_b32 s17, s17, 15
	s_lshl_b32 s16, s18, 3
	s_add_i32 s16, s16, 0x7be00
	v_mov_b32_e32 v2, 0x23fd8
	ds_read_b64 v[2:3], v2
	s_waitcnt lgkmcnt(0)
	v_readfirstlane_b32 s4, v2
	v_readfirstlane_b32 s5, v3
	s_branch .Lmy_cv_entry
